# FoX unit set-up: decay table filled with all 32 candidate entries per thread fetched at once (was two dependent loads per round trip)
# speedup vs baseline: 1.0146x; 1.0146x over previous
; #define q_cum ((float*)(karg_ws() + WS_CUM))
; template<int MODE,int THRL> __device__ __forceinline__ void attn_unit(int qb,const bf16*Q,const bf16*__restrict__ K,const bf16*__restrict__ V,bf16*O,const float*__restrict__ cum,const float*__restrict__ relb,const float thr,char*shm,const int wv){
;     ...
;   const int q0=qb*QB;
;   const bf16*Qw=Q+(long)(q0+wid*QBLK)*PITCH;
;   typedef __attribute__((address_space(3))) float* lds_fptr;
;   const lds_fptr kb3=(lds_fptr)(__attribute__((address_space(3))) char*)shm+LDS_KB/4;
;   if constexpr(MODE==0){ const float cref=cum[q0]; for(int i=tid;i<q0+QB;i+=NW*64)kb3[i]=(cref-cum[i])*1.4426950408889634f; }
; template <int l, int SEL> __device__ __forceinline__ void layer_body(const Args& args, LAS unsigned char* ldsp, unsigned char* lds, const int G, const int bx, const int vcu, const int wv) {
;     ...
;                 for (int half = 0; half < 2; ++half) { const int qb = half ? 63 - s : s;
;                     attn_body::attn_unit<0, 8>(qb, pj + (size_t)vh * M * 64, pj + (size_t)(8 + vh) * M * 64, pj + (size_t)(16 + vh) * M * 64, (abf*)q_yatt + vh * 64, q_cum + (size_t)vh * M, nullptr, thr, (char*)lds, wv); } }
.LBB0_367:
	s_mov_b64 s[4:5], s[0:1]
	s_load_dwordx2 s[52:53], s[4:5], 0xc0
	s_and_b64 s[4:5], s[6:7], exec
	s_mov_b64 s[54:55], s[0:1]
	s_cselect_b32 s12, s96, s97
	v_mbcnt_lo_u32_b32 v34, -1, 0
	v_mbcnt_hi_u32_b32 v34, -1, v34
	s_add_i32 s19, s12, 0x100
	v_or_b32_e32 v2, s69, v34
	v_cmp_gt_i32_e32 vcc, s19, v2
	s_and_saveexec_b64 s[4:5], vcc
	s_cbranch_execz .LBB0_375
; template<int MODE,int THRL> __device__ __forceinline__ void attn_unit(int qb,const bf16*Q,const bf16*__restrict__ K,const bf16*__restrict__ V,bf16*O,const float*__restrict__ cum,const float*__restrict__ relb,const float thr,char*shm,const int wv){
;     ...
;   if constexpr(MODE==0){ const float cref=cum[q0]; for(int i=tid;i<q0+QB;i+=NW*64)kb3[i]=(cref-cum[i])*1.4426950408889634f; }
	s_load_dwordx2 s[40:41], s[54:55], 0xc0
	v_add_u32_e32 v3, 0x200, v2
	s_mov_b64 s[58:59], -1
	v_mov_b32_e32 v6, v2
	s_waitcnt lgkmcnt(0)
	s_add_u32 s21, s40, s48
	s_addc_u32 s40, s41, s49
	s_add_u32 s54, s21, 0x200000
	s_addc_u32 s55, s40, 0
	s_lshl_b32 s21, s12, 2
	v_mov_b32_e32 v0, s21
	global_load_dword v4, v0, s[54:55]
	v_lshlrev_b32_e32 v132, 2, v2
	s_mov_b64 s[56:57], s[54:55]
	global_load_dword v100, v132, s[56:57]
	s_add_u32 s56, s56, 0x800
	s_addc_u32 s57, s57, 0
	global_load_dword v101, v132, s[56:57]
	s_add_u32 s56, s56, 0x800
	s_addc_u32 s57, s57, 0
	global_load_dword v102, v132, s[56:57]
	s_add_u32 s56, s56, 0x800
	s_addc_u32 s57, s57, 0
	global_load_dword v103, v132, s[56:57]
	s_add_u32 s56, s56, 0x800
	s_addc_u32 s57, s57, 0
	global_load_dword v104, v132, s[56:57]
	s_add_u32 s56, s56, 0x800
	s_addc_u32 s57, s57, 0
	global_load_dword v105, v132, s[56:57]
	s_add_u32 s56, s56, 0x800
	s_addc_u32 s57, s57, 0
	global_load_dword v106, v132, s[56:57]
	s_add_u32 s56, s56, 0x800
	s_addc_u32 s57, s57, 0
	global_load_dword v107, v132, s[56:57]
	s_add_u32 s56, s56, 0x800
	s_addc_u32 s57, s57, 0
	global_load_dword v108, v132, s[56:57]
	s_add_u32 s56, s56, 0x800
	s_addc_u32 s57, s57, 0
	global_load_dword v109, v132, s[56:57]
	s_add_u32 s56, s56, 0x800
	s_addc_u32 s57, s57, 0
	global_load_dword v110, v132, s[56:57]
	s_add_u32 s56, s56, 0x800
	s_addc_u32 s57, s57, 0
	global_load_dword v111, v132, s[56:57]
	s_add_u32 s56, s56, 0x800
	s_addc_u32 s57, s57, 0
	global_load_dword v112, v132, s[56:57]
	s_add_u32 s56, s56, 0x800
	s_addc_u32 s57, s57, 0
	global_load_dword v113, v132, s[56:57]
	s_add_u32 s56, s56, 0x800
	s_addc_u32 s57, s57, 0
	global_load_dword v114, v132, s[56:57]
	s_add_u32 s56, s56, 0x800
	s_addc_u32 s57, s57, 0
	global_load_dword v115, v132, s[56:57]
	s_add_u32 s56, s56, 0x800
	s_addc_u32 s57, s57, 0
	global_load_dword v116, v132, s[56:57]
	s_add_u32 s56, s56, 0x800
	s_addc_u32 s57, s57, 0
	global_load_dword v117, v132, s[56:57]
	s_add_u32 s56, s56, 0x800
	s_addc_u32 s57, s57, 0
	global_load_dword v118, v132, s[56:57]
	s_add_u32 s56, s56, 0x800
	s_addc_u32 s57, s57, 0
	global_load_dword v119, v132, s[56:57]
	s_add_u32 s56, s56, 0x800
	s_addc_u32 s57, s57, 0
	global_load_dword v120, v132, s[56:57]
	s_add_u32 s56, s56, 0x800
	s_addc_u32 s57, s57, 0
	global_load_dword v121, v132, s[56:57]
	s_add_u32 s56, s56, 0x800
	s_addc_u32 s57, s57, 0
	global_load_dword v122, v132, s[56:57]
	s_add_u32 s56, s56, 0x800
	s_addc_u32 s57, s57, 0
	global_load_dword v123, v132, s[56:57]
	s_add_u32 s56, s56, 0x800
	s_addc_u32 s57, s57, 0
	global_load_dword v124, v132, s[56:57]
	s_add_u32 s56, s56, 0x800
	s_addc_u32 s57, s57, 0
	global_load_dword v125, v132, s[56:57]
	s_add_u32 s56, s56, 0x800
	s_addc_u32 s57, s57, 0
	global_load_dword v126, v132, s[56:57]
	s_add_u32 s56, s56, 0x800
	s_addc_u32 s57, s57, 0
	global_load_dword v127, v132, s[56:57]
	s_add_u32 s56, s56, 0x800
	s_addc_u32 s57, s57, 0
	global_load_dword v128, v132, s[56:57]
	s_add_u32 s56, s56, 0x800
	s_addc_u32 s57, s57, 0
	global_load_dword v129, v132, s[56:57]
	s_add_u32 s56, s56, 0x800
	s_addc_u32 s57, s57, 0
	global_load_dword v130, v132, s[56:57]
	s_add_u32 s56, s56, 0x800
	s_addc_u32 s57, s57, 0
	global_load_dword v131, v132, s[56:57]
	s_add_u32 s56, s56, 0x800
	s_addc_u32 s57, s57, 0
	v_add_u32_e32 v133, s87, v132
	s_waitcnt vmcnt(0)
	v_sub_f32_e32 v134, v4, v100
	v_mul_f32_e32 v134, 0x3fb8aa3b, v134
	ds_write_b32 v133, v134
	v_sub_f32_e32 v135, v4, v101
	v_mul_f32_e32 v135, 0x3fb8aa3b, v135
	ds_write_b32 v133, v135 offset:2048
	v_sub_f32_e32 v136, v4, v102
	v_mul_f32_e32 v136, 0x3fb8aa3b, v136
	ds_write_b32 v133, v136 offset:4096
	v_sub_f32_e32 v137, v4, v103
	v_mul_f32_e32 v137, 0x3fb8aa3b, v137
	ds_write_b32 v133, v137 offset:6144
	v_sub_f32_e32 v134, v4, v104
	v_mul_f32_e32 v134, 0x3fb8aa3b, v134
	ds_write_b32 v133, v134 offset:8192
	v_sub_f32_e32 v135, v4, v105
	v_mul_f32_e32 v135, 0x3fb8aa3b, v135
	ds_write_b32 v133, v135 offset:10240
	v_sub_f32_e32 v136, v4, v106
	v_mul_f32_e32 v136, 0x3fb8aa3b, v136
	ds_write_b32 v133, v136 offset:12288
	v_sub_f32_e32 v137, v4, v107
	v_mul_f32_e32 v137, 0x3fb8aa3b, v137
	ds_write_b32 v133, v137 offset:14336
	v_sub_f32_e32 v134, v4, v108
	v_mul_f32_e32 v134, 0x3fb8aa3b, v134
	ds_write_b32 v133, v134 offset:16384
	v_sub_f32_e32 v135, v4, v109
	v_mul_f32_e32 v135, 0x3fb8aa3b, v135
	ds_write_b32 v133, v135 offset:18432
	v_sub_f32_e32 v136, v4, v110
	v_mul_f32_e32 v136, 0x3fb8aa3b, v136
	ds_write_b32 v133, v136 offset:20480
	v_sub_f32_e32 v137, v4, v111
	v_mul_f32_e32 v137, 0x3fb8aa3b, v137
	ds_write_b32 v133, v137 offset:22528
	v_sub_f32_e32 v134, v4, v112
	v_mul_f32_e32 v134, 0x3fb8aa3b, v134
	ds_write_b32 v133, v134 offset:24576
	v_sub_f32_e32 v135, v4, v113
	v_mul_f32_e32 v135, 0x3fb8aa3b, v135
	ds_write_b32 v133, v135 offset:26624
	v_sub_f32_e32 v136, v4, v114
	v_mul_f32_e32 v136, 0x3fb8aa3b, v136
	ds_write_b32 v133, v136 offset:28672
	v_sub_f32_e32 v137, v4, v115
	v_mul_f32_e32 v137, 0x3fb8aa3b, v137
	ds_write_b32 v133, v137 offset:30720
	v_sub_f32_e32 v134, v4, v116
	v_mul_f32_e32 v134, 0x3fb8aa3b, v134
	ds_write_b32 v133, v134 offset:32768
	v_sub_f32_e32 v135, v4, v117
	v_mul_f32_e32 v135, 0x3fb8aa3b, v135
	ds_write_b32 v133, v135 offset:34816
	v_sub_f32_e32 v136, v4, v118
	v_mul_f32_e32 v136, 0x3fb8aa3b, v136
	ds_write_b32 v133, v136 offset:36864
	v_sub_f32_e32 v137, v4, v119
	v_mul_f32_e32 v137, 0x3fb8aa3b, v137
	ds_write_b32 v133, v137 offset:38912
	v_sub_f32_e32 v134, v4, v120
	v_mul_f32_e32 v134, 0x3fb8aa3b, v134
	ds_write_b32 v133, v134 offset:40960
	v_sub_f32_e32 v135, v4, v121
	v_mul_f32_e32 v135, 0x3fb8aa3b, v135
	ds_write_b32 v133, v135 offset:43008
	v_sub_f32_e32 v136, v4, v122
	v_mul_f32_e32 v136, 0x3fb8aa3b, v136
	ds_write_b32 v133, v136 offset:45056
	v_sub_f32_e32 v137, v4, v123
	v_mul_f32_e32 v137, 0x3fb8aa3b, v137
	ds_write_b32 v133, v137 offset:47104
	v_sub_f32_e32 v134, v4, v124
	v_mul_f32_e32 v134, 0x3fb8aa3b, v134
	ds_write_b32 v133, v134 offset:49152
	v_sub_f32_e32 v135, v4, v125
	v_mul_f32_e32 v135, 0x3fb8aa3b, v135
	ds_write_b32 v133, v135 offset:51200
	v_sub_f32_e32 v136, v4, v126
	v_mul_f32_e32 v136, 0x3fb8aa3b, v136
	ds_write_b32 v133, v136 offset:53248
	v_sub_f32_e32 v137, v4, v127
	v_mul_f32_e32 v137, 0x3fb8aa3b, v137
	ds_write_b32 v133, v137 offset:55296
	v_sub_f32_e32 v134, v4, v128
	v_mul_f32_e32 v134, 0x3fb8aa3b, v134
	ds_write_b32 v133, v134 offset:57344
	v_sub_f32_e32 v135, v4, v129
	v_mul_f32_e32 v135, 0x3fb8aa3b, v135
	ds_write_b32 v133, v135 offset:59392
	v_sub_f32_e32 v136, v4, v130
	v_mul_f32_e32 v136, 0x3fb8aa3b, v136
	ds_write_b32 v133, v136 offset:61440
	v_sub_f32_e32 v137, v4, v131
	v_mul_f32_e32 v137, 0x3fb8aa3b, v137
	ds_write_b32 v133, v137 offset:63488

; #define q_cum ((float*)(karg_ws() + WS_CUM))
; template<int MODE,int THRL> __device__ __forceinline__ void attn_unit(int qb,const bf16*Q,const bf16*__restrict__ K,const bf16*__restrict__ V,bf16*O,const float*__restrict__ cum,const float*__restrict__ relb,const float thr,char*shm,const int wv){
;     ...
;   const int q0=qb*QB;
;   const bf16*Qw=Q+(long)(q0+wid*QBLK)*PITCH;
;   typedef __attribute__((address_space(3))) float* lds_fptr;
;   const lds_fptr kb3=(lds_fptr)(__attribute__((address_space(3))) char*)shm+LDS_KB/4;
;   if constexpr(MODE==0){ const float cref=cum[q0]; for(int i=tid;i<q0+QB;i+=NW*64)kb3[i]=(cref-cum[i])*1.4426950408889634f; }
; template <int l, int SEL> __device__ __forceinline__ void layer_body(const Args& args, LAS unsigned char* ldsp, unsigned char* lds, const int G, const int bx, const int vcu, const int wv) {
;     ...
;                 for (int half = 0; half < 2; ++half) { const int qb = half ? 63 - s : s;
;                     attn_body::attn_unit<0, 8>(qb, pj + (size_t)vh * M * 64, pj + (size_t)(8 + vh) * M * 64, pj + (size_t)(16 + vh) * M * 64, (abf*)q_yatt + vh * 64, q_cum + (size_t)vh * M, nullptr, thr, (char*)lds, wv); } }
.LBB0_1407:
	s_mov_b64 s[8:9], s[0:1]
	s_load_dwordx2 s[50:51], s[8:9], 0xc0
	s_and_b64 s[8:9], s[10:11], exec
	s_mov_b64 s[52:53], s[0:1]
	s_cselect_b32 s14, s93, s94
	v_mbcnt_lo_u32_b32 v34, -1, 0
	v_mbcnt_hi_u32_b32 v34, -1, v34
	s_add_i32 s21, s14, 0x100
	v_or_b32_e32 v2, s69, v34
	v_cmp_gt_i32_e32 vcc, s21, v2
	s_and_saveexec_b64 s[8:9], vcc
	s_cbranch_execz .LBB0_1415
; template<int MODE,int THRL> __device__ __forceinline__ void attn_unit(int qb,const bf16*Q,const bf16*__restrict__ K,const bf16*__restrict__ V,bf16*O,const float*__restrict__ cum,const float*__restrict__ relb,const float thr,char*shm,const int wv){
;     ...
;   if constexpr(MODE==0){ const float cref=cum[q0]; for(int i=tid;i<q0+QB;i+=NW*64)kb3[i]=(cref-cum[i])*1.4426950408889634f; }
	s_load_dwordx2 s[52:53], s[52:53], 0xc0
	v_add_u32_e32 v3, 0x200, v2
	s_mov_b64 s[56:57], -1
	v_mov_b32_e32 v6, v2
	s_waitcnt lgkmcnt(0)
	s_add_u32 s23, s52, s46
	s_addc_u32 s53, s53, s47
	s_add_u32 s52, s23, 0x200000
	s_addc_u32 s53, s53, 0
	s_lshl_b32 s23, s14, 2
	v_mov_b32_e32 v0, s23
	global_load_dword v4, v0, s[52:53]
	v_lshlrev_b32_e32 v132, 2, v2
	s_mov_b64 s[56:57], s[52:53]
	global_load_dword v100, v132, s[56:57]
	s_add_u32 s56, s56, 0x800
	s_addc_u32 s57, s57, 0
	global_load_dword v101, v132, s[56:57]
	s_add_u32 s56, s56, 0x800
	s_addc_u32 s57, s57, 0
	global_load_dword v102, v132, s[56:57]
	s_add_u32 s56, s56, 0x800
	s_addc_u32 s57, s57, 0
	global_load_dword v103, v132, s[56:57]
	s_add_u32 s56, s56, 0x800
	s_addc_u32 s57, s57, 0
	global_load_dword v104, v132, s[56:57]
	s_add_u32 s56, s56, 0x800
	s_addc_u32 s57, s57, 0
	global_load_dword v105, v132, s[56:57]
	s_add_u32 s56, s56, 0x800
	s_addc_u32 s57, s57, 0
	global_load_dword v106, v132, s[56:57]
	s_add_u32 s56, s56, 0x800
	s_addc_u32 s57, s57, 0
	global_load_dword v107, v132, s[56:57]
	s_add_u32 s56, s56, 0x800
	s_addc_u32 s57, s57, 0
	global_load_dword v108, v132, s[56:57]
	s_add_u32 s56, s56, 0x800
	s_addc_u32 s57, s57, 0
	global_load_dword v109, v132, s[56:57]
	s_add_u32 s56, s56, 0x800
	s_addc_u32 s57, s57, 0
	global_load_dword v110, v132, s[56:57]
	s_add_u32 s56, s56, 0x800
	s_addc_u32 s57, s57, 0
	global_load_dword v111, v132, s[56:57]
	s_add_u32 s56, s56, 0x800
	s_addc_u32 s57, s57, 0
	global_load_dword v112, v132, s[56:57]
	s_add_u32 s56, s56, 0x800
	s_addc_u32 s57, s57, 0
	global_load_dword v113, v132, s[56:57]
	s_add_u32 s56, s56, 0x800
	s_addc_u32 s57, s57, 0
	global_load_dword v114, v132, s[56:57]
	s_add_u32 s56, s56, 0x800
	s_addc_u32 s57, s57, 0
	global_load_dword v115, v132, s[56:57]
	s_add_u32 s56, s56, 0x800
	s_addc_u32 s57, s57, 0
	global_load_dword v116, v132, s[56:57]
	s_add_u32 s56, s56, 0x800
	s_addc_u32 s57, s57, 0
	global_load_dword v117, v132, s[56:57]
	s_add_u32 s56, s56, 0x800
	s_addc_u32 s57, s57, 0
	global_load_dword v118, v132, s[56:57]
	s_add_u32 s56, s56, 0x800
	s_addc_u32 s57, s57, 0
	global_load_dword v119, v132, s[56:57]
	s_add_u32 s56, s56, 0x800
	s_addc_u32 s57, s57, 0
	global_load_dword v120, v132, s[56:57]
	s_add_u32 s56, s56, 0x800
	s_addc_u32 s57, s57, 0
	global_load_dword v121, v132, s[56:57]
	s_add_u32 s56, s56, 0x800
	s_addc_u32 s57, s57, 0
	global_load_dword v122, v132, s[56:57]
	s_add_u32 s56, s56, 0x800
	s_addc_u32 s57, s57, 0
	global_load_dword v123, v132, s[56:57]
	s_add_u32 s56, s56, 0x800
	s_addc_u32 s57, s57, 0
	global_load_dword v124, v132, s[56:57]
	s_add_u32 s56, s56, 0x800
	s_addc_u32 s57, s57, 0
	global_load_dword v125, v132, s[56:57]
	s_add_u32 s56, s56, 0x800
	s_addc_u32 s57, s57, 0
	global_load_dword v126, v132, s[56:57]
	s_add_u32 s56, s56, 0x800
	s_addc_u32 s57, s57, 0
	global_load_dword v127, v132, s[56:57]
	s_add_u32 s56, s56, 0x800
	s_addc_u32 s57, s57, 0
	global_load_dword v128, v132, s[56:57]
	s_add_u32 s56, s56, 0x800
	s_addc_u32 s57, s57, 0
	global_load_dword v129, v132, s[56:57]
	s_add_u32 s56, s56, 0x800
	s_addc_u32 s57, s57, 0
	global_load_dword v130, v132, s[56:57]
	s_add_u32 s56, s56, 0x800
	s_addc_u32 s57, s57, 0
	global_load_dword v131, v132, s[56:57]
	s_add_u32 s56, s56, 0x800
	s_addc_u32 s57, s57, 0
	v_add_u32_e32 v133, s84, v132
	s_waitcnt vmcnt(0)
	v_sub_f32_e32 v134, v4, v100
	v_mul_f32_e32 v134, 0x3fb8aa3b, v134
	ds_write_b32 v133, v134
	v_sub_f32_e32 v135, v4, v101
	v_mul_f32_e32 v135, 0x3fb8aa3b, v135
	ds_write_b32 v133, v135 offset:2048
	v_sub_f32_e32 v136, v4, v102
	v_mul_f32_e32 v136, 0x3fb8aa3b, v136
	ds_write_b32 v133, v136 offset:4096
	v_sub_f32_e32 v137, v4, v103
	v_mul_f32_e32 v137, 0x3fb8aa3b, v137
	ds_write_b32 v133, v137 offset:6144
	v_sub_f32_e32 v134, v4, v104
	v_mul_f32_e32 v134, 0x3fb8aa3b, v134
	ds_write_b32 v133, v134 offset:8192
	v_sub_f32_e32 v135, v4, v105
	v_mul_f32_e32 v135, 0x3fb8aa3b, v135
	ds_write_b32 v133, v135 offset:10240
	v_sub_f32_e32 v136, v4, v106
	v_mul_f32_e32 v136, 0x3fb8aa3b, v136
	ds_write_b32 v133, v136 offset:12288
	v_sub_f32_e32 v137, v4, v107
	v_mul_f32_e32 v137, 0x3fb8aa3b, v137
	ds_write_b32 v133, v137 offset:14336
	v_sub_f32_e32 v134, v4, v108
	v_mul_f32_e32 v134, 0x3fb8aa3b, v134
	ds_write_b32 v133, v134 offset:16384
	v_sub_f32_e32 v135, v4, v109
	v_mul_f32_e32 v135, 0x3fb8aa3b, v135
	ds_write_b32 v133, v135 offset:18432
	v_sub_f32_e32 v136, v4, v110
	v_mul_f32_e32 v136, 0x3fb8aa3b, v136
	ds_write_b32 v133, v136 offset:20480
	v_sub_f32_e32 v137, v4, v111
	v_mul_f32_e32 v137, 0x3fb8aa3b, v137
	ds_write_b32 v133, v137 offset:22528
	v_sub_f32_e32 v134, v4, v112
	v_mul_f32_e32 v134, 0x3fb8aa3b, v134
	ds_write_b32 v133, v134 offset:24576
	v_sub_f32_e32 v135, v4, v113
	v_mul_f32_e32 v135, 0x3fb8aa3b, v135
	ds_write_b32 v133, v135 offset:26624
	v_sub_f32_e32 v136, v4, v114
	v_mul_f32_e32 v136, 0x3fb8aa3b, v136
	ds_write_b32 v133, v136 offset:28672
	v_sub_f32_e32 v137, v4, v115
	v_mul_f32_e32 v137, 0x3fb8aa3b, v137
	ds_write_b32 v133, v137 offset:30720
	v_sub_f32_e32 v134, v4, v116
	v_mul_f32_e32 v134, 0x3fb8aa3b, v134
	ds_write_b32 v133, v134 offset:32768
	v_sub_f32_e32 v135, v4, v117
	v_mul_f32_e32 v135, 0x3fb8aa3b, v135
	ds_write_b32 v133, v135 offset:34816
	v_sub_f32_e32 v136, v4, v118
	v_mul_f32_e32 v136, 0x3fb8aa3b, v136
	ds_write_b32 v133, v136 offset:36864
	v_sub_f32_e32 v137, v4, v119
	v_mul_f32_e32 v137, 0x3fb8aa3b, v137
	ds_write_b32 v133, v137 offset:38912
	v_sub_f32_e32 v134, v4, v120
	v_mul_f32_e32 v134, 0x3fb8aa3b, v134
	ds_write_b32 v133, v134 offset:40960
	v_sub_f32_e32 v135, v4, v121
	v_mul_f32_e32 v135, 0x3fb8aa3b, v135
	ds_write_b32 v133, v135 offset:43008
	v_sub_f32_e32 v136, v4, v122
	v_mul_f32_e32 v136, 0x3fb8aa3b, v136
	ds_write_b32 v133, v136 offset:45056
	v_sub_f32_e32 v137, v4, v123
	v_mul_f32_e32 v137, 0x3fb8aa3b, v137
	ds_write_b32 v133, v137 offset:47104
	v_sub_f32_e32 v134, v4, v124
	v_mul_f32_e32 v134, 0x3fb8aa3b, v134
	ds_write_b32 v133, v134 offset:49152
	v_sub_f32_e32 v135, v4, v125
	v_mul_f32_e32 v135, 0x3fb8aa3b, v135
	ds_write_b32 v133, v135 offset:51200
	v_sub_f32_e32 v136, v4, v126
	v_mul_f32_e32 v136, 0x3fb8aa3b, v136
	ds_write_b32 v133, v136 offset:53248
	v_sub_f32_e32 v137, v4, v127
	v_mul_f32_e32 v137, 0x3fb8aa3b, v137
	ds_write_b32 v133, v137 offset:55296
	v_sub_f32_e32 v134, v4, v128
	v_mul_f32_e32 v134, 0x3fb8aa3b, v134
	ds_write_b32 v133, v134 offset:57344
	v_sub_f32_e32 v135, v4, v129
	v_mul_f32_e32 v135, 0x3fb8aa3b, v135
	ds_write_b32 v133, v135 offset:59392
	v_sub_f32_e32 v136, v4, v130
	v_mul_f32_e32 v136, 0x3fb8aa3b, v136
	ds_write_b32 v133, v136 offset:61440
	v_sub_f32_e32 v137, v4, v131
	v_mul_f32_e32 v137, 0x3fb8aa3b, v137
	ds_write_b32 v133, v137 offset:63488
